# v84 + in-proj GEMM: first K-loop iteration of every unit after the first peeled into a copy whose first two counted waits (vmcnt 8 -> 24) no longer force the previous unit's 16 epilogue stores to reti
# baseline (speedup 1.0000x reference)
.LBB0_720:
	s_ashr_i32 s29, s28, 31
	s_lshl_b64 s[4:5], s[28:29], 18
	s_add_u32 s34, s14, s4
	s_addc_u32 s35, s15, s5
	s_and_b64 s[4:5], s[36:37], exec
	s_cselect_b32 s17, s35, s3
	s_cselect_b32 s29, s34, s2
	s_cmp_eq_u32 s8, 0
	s_cselect_b64 s[4:5], -1, 0
	s_and_b64 s[6:7], s[4:5], exec
	s_cselect_b32 s64, 0x40000, 0
	s_cmp_eq_u32 s52, 0
	s_cselect_b32 s12, 0x40000, 0
	s_ashr_i32 s31, s30, 31
	s_lshl_b64 s[6:7], s[30:31], 19
	v_readlane_b32 s8, v255, 9
	s_add_u32 s40, s8, s6
	v_readlane_b32 s6, v255, 10
	s_addc_u32 s41, s6, s7
	s_and_b64 s[6:7], s[36:37], exec
	s_cselect_b32 s13, s41, s1
	s_cselect_b32 s31, s40, s0
	s_add_u32 s96, s0, 0x100
	s_addc_u32 s97, s1, 0
	s_add_u32 s0, s2, 0x80
	s_addc_u32 s1, s3, 0
	v_lshl_add_u64 v[0:1], s[0:1], 0, v[206:207]
	v_lshl_add_u64 v[210:211], v[0:1], 0, s[64:65]
	v_lshl_add_u64 v[0:1], s[0:1], 0, v[208:209]
	v_mov_b32_e32 v160, v161
	v_lshl_add_u64 v[212:213], v[0:1], 0, s[64:65]
	s_waitcnt lgkmcnt(0)
	v_mov_b32_e32 v162, v161
	v_mov_b32_e32 v163, v161
	v_mov_b32_e32 v64, 0
	v_mov_b64_e32 v[0:1], v[160:161]
	v_mov_b64_e32 v[4:5], v[160:161]
	v_mov_b64_e32 v[16:17], v[160:161]
	v_mov_b64_e32 v[20:21], v[160:161]
	v_mov_b64_e32 v[32:33], v[160:161]
	v_mov_b64_e32 v[36:37], v[160:161]
	v_mov_b64_e32 v[48:49], v[160:161]
	v_mov_b64_e32 v[52:53], v[160:161]
	v_mov_b64_e32 v[8:9], v[160:161]
	v_mov_b64_e32 v[12:13], v[160:161]
	v_mov_b64_e32 v[24:25], v[160:161]
	v_mov_b64_e32 v[28:29], v[160:161]
	v_mov_b64_e32 v[40:41], v[160:161]
	v_mov_b64_e32 v[44:45], v[160:161]
	v_mov_b64_e32 v[56:57], v[160:161]
	v_mov_b64_e32 v[60:61], v[160:161]
	s_mov_b32 s54, -2
	s_mov_b64 s[6:7], 0
	v_mov_b64_e32 v[2:3], v[162:163]
	v_mov_b64_e32 v[6:7], v[162:163]
	v_mov_b64_e32 v[18:19], v[162:163]
	v_mov_b64_e32 v[22:23], v[162:163]
	v_mov_b64_e32 v[34:35], v[162:163]
	v_mov_b64_e32 v[38:39], v[162:163]
	v_mov_b64_e32 v[50:51], v[162:163]
	v_mov_b64_e32 v[54:55], v[162:163]
	v_mov_b64_e32 v[10:11], v[162:163]
	v_mov_b64_e32 v[14:15], v[162:163]
	v_mov_b64_e32 v[26:27], v[162:163]
	v_mov_b64_e32 v[30:31], v[162:163]
	v_mov_b64_e32 v[42:43], v[162:163]
	v_mov_b64_e32 v[46:47], v[162:163]
	v_mov_b64_e32 v[58:59], v[162:163]
	v_mov_b64_e32 v[62:63], v[162:163]
	v_mov_b32_e32 v65, v64
	v_mov_b32_e32 v66, v64
	v_mov_b32_e32 v67, v64
	v_mov_b32_e32 v68, v64
	v_mov_b32_e32 v69, v64
	v_mov_b32_e32 v70, v64
	v_mov_b32_e32 v71, v64
	v_mov_b32_e32 v80, v64
	v_mov_b32_e32 v81, v64
	v_mov_b32_e32 v82, v64
	v_mov_b32_e32 v83, v64
	v_mov_b32_e32 v84, v64
	v_mov_b32_e32 v85, v64
	v_mov_b32_e32 v86, v64
	v_mov_b32_e32 v87, v64
	v_mov_b32_e32 v96, v64
	v_mov_b32_e32 v97, v64
	v_mov_b32_e32 v98, v64
	v_mov_b32_e32 v99, v64
	v_mov_b32_e32 v100, v64
	v_mov_b32_e32 v101, v64
	v_mov_b32_e32 v102, v64
	v_mov_b32_e32 v103, v64
	v_mov_b32_e32 v112, v64
	v_mov_b32_e32 v113, v64
	v_mov_b32_e32 v114, v64
	v_mov_b32_e32 v115, v64
	v_mov_b32_e32 v116, v64
	v_mov_b32_e32 v117, v64
	v_mov_b32_e32 v118, v64
	v_mov_b32_e32 v119, v64
	v_mov_b32_e32 v72, v64
	v_mov_b32_e32 v73, v64
	v_mov_b32_e32 v74, v64
	v_mov_b32_e32 v75, v64
	v_mov_b32_e32 v76, v64
	v_mov_b32_e32 v77, v64
	v_mov_b32_e32 v78, v64
	v_mov_b32_e32 v79, v64
	v_mov_b32_e32 v88, v64
	v_mov_b32_e32 v89, v64
	v_mov_b32_e32 v90, v64
	v_mov_b32_e32 v91, v64
	v_mov_b32_e32 v92, v64
	v_mov_b32_e32 v93, v64
	v_mov_b32_e32 v94, v64
	v_mov_b32_e32 v95, v64
	v_mov_b32_e32 v104, v64
	v_mov_b32_e32 v105, v64
	v_mov_b32_e32 v106, v64
	v_mov_b32_e32 v107, v64
	v_mov_b32_e32 v108, v64
	v_mov_b32_e32 v109, v64
	v_mov_b32_e32 v110, v64
	v_mov_b32_e32 v111, v64
	v_mov_b32_e32 v120, v64
	v_mov_b32_e32 v121, v64
	v_mov_b32_e32 v122, v64
	v_mov_b32_e32 v123, v64
	v_mov_b32_e32 v124, v64
	v_mov_b32_e32 v125, v64
	v_mov_b32_e32 v126, v64
	v_mov_b32_e32 v127, v64
	s_cmp_eq_u32 s49, 1
	s_cbranch_scc1 .LBB0_722
	s_branch .Lp6_head

.Lp6_head:
	s_add_u32 s0, s2, s6
	s_addc_u32 s1, s3, s7
	s_add_u32 s8, s0, 0x100
	s_addc_u32 s9, s1, 0
	s_add_u32 s55, s96, s6
	s_addc_u32 vcc_lo, s97, s7
	s_add_i32 vcc_hi, 16, 0x10000
	s_cmpk_eq_i32 s6, 0x700
	s_cselect_b64 s[38:39], -1, 0
	s_and_b64 s[0:1], s[38:39], exec
	s_cselect_b32 s11, s17, s9
	s_cselect_b32 s10, s29, s8
	s_cselect_b32 s9, s13, vcc_lo
	s_cselect_b32 s8, s31, s55
	s_add_i32 s55, 16, 0x14000
	v_add_u32_e32 v128, vcc_hi, v203
	v_add_u32_e32 v140, s55, v203
	ds_read_b128 v[144:147], v128
	ds_read_b128 v[148:151], v128 offset:1024
	ds_read_b128 v[152:155], v128 offset:2048
	ds_read_b128 v[156:159], v128 offset:3072
	ds_read_b128 v[128:131], v140
	ds_read_b128 v[132:135], v140 offset:1024
	ds_read_b128 v[136:139], v140 offset:2048
	ds_read_b128 v[140:143], v140 offset:3072
	v_lshl_add_u64 v[214:215], v[212:213], 0, s[6:7]
	s_add_i32 m0, s21, 0xc000
	s_waitcnt lgkmcnt(0)
	ds_read_b128 v[162:165], v223
	ds_read_b128 v[166:169], v223 offset:1024
	ds_read_b128 v[170:173], v223 offset:2048
	ds_read_b128 v[174:177], v223 offset:3072
	ds_read_b128 v[178:181], v223 offset:4096
	ds_read_b128 v[182:185], v223 offset:5120
	ds_read_b128 v[186:189], v223 offset:6144
	ds_read_b128 v[190:193], v223 offset:7168
	global_load_lds_dwordx4 v[214:215], off
	v_lshl_add_u64 v[214:215], v[210:211], 0, s[6:7]
	s_add_i32 m0, s21, 0xe000
	s_nop 0
	global_load_lds_dwordx4 v[214:215], off
	s_waitcnt vmcnt(24)
	s_waitcnt lgkmcnt(0)
	s_barrier
	s_setprio 1
	v_mfma_f32_16x16x32_bf16 v[124:127], v[144:147], v[162:165], v[124:127]
	v_mfma_f32_16x16x32_bf16 v[120:123], v[152:155], v[162:165], v[120:123]
	v_mfma_f32_16x16x32_bf16 v[108:111], v[144:147], v[170:173], v[108:111]
	v_mfma_f32_16x16x32_bf16 v[104:107], v[152:155], v[170:173], v[104:107]
	v_mfma_f32_16x16x32_bf16 v[92:95], v[144:147], v[178:181], v[92:95]
	v_mfma_f32_16x16x32_bf16 v[88:91], v[152:155], v[178:181], v[88:91]
	v_mfma_f32_16x16x32_bf16 v[76:79], v[144:147], v[186:189], v[76:79]
	v_mfma_f32_16x16x32_bf16 v[72:75], v[152:155], v[186:189], v[72:75]
	v_mfma_f32_16x16x32_bf16 v[124:127], v[148:151], v[166:169], v[124:127]
	v_mfma_f32_16x16x32_bf16 v[120:123], v[156:159], v[166:169], v[120:123]
	v_mfma_f32_16x16x32_bf16 v[108:111], v[148:151], v[174:177], v[108:111]
	v_mfma_f32_16x16x32_bf16 v[104:107], v[156:159], v[174:177], v[104:107]
	v_mfma_f32_16x16x32_bf16 v[92:95], v[148:151], v[182:185], v[92:95]
	v_mfma_f32_16x16x32_bf16 v[88:91], v[156:159], v[182:185], v[88:91]
	v_mfma_f32_16x16x32_bf16 v[76:79], v[148:151], v[190:193], v[76:79]
	v_mfma_f32_16x16x32_bf16 v[72:75], v[156:159], v[190:193], v[72:75]
	s_setprio 0
	s_setprio 1
	v_mfma_f32_16x16x32_bf16 v[116:119], v[128:131], v[162:165], v[116:119]
	v_mfma_f32_16x16x32_bf16 v[112:115], v[136:139], v[162:165], v[112:115]
	v_mfma_f32_16x16x32_bf16 v[100:103], v[128:131], v[170:173], v[100:103]
	v_mfma_f32_16x16x32_bf16 v[96:99], v[136:139], v[170:173], v[96:99]
	v_mfma_f32_16x16x32_bf16 v[84:87], v[128:131], v[178:181], v[84:87]
	v_mfma_f32_16x16x32_bf16 v[80:83], v[136:139], v[178:181], v[80:83]
	v_mfma_f32_16x16x32_bf16 v[68:71], v[128:131], v[186:189], v[68:71]
	v_mfma_f32_16x16x32_bf16 v[64:67], v[136:139], v[186:189], v[64:67]
	v_mfma_f32_16x16x32_bf16 v[116:119], v[132:135], v[166:169], v[116:119]
	v_mfma_f32_16x16x32_bf16 v[112:115], v[140:143], v[166:169], v[112:115]
	v_mfma_f32_16x16x32_bf16 v[100:103], v[132:135], v[174:177], v[100:103]
	v_mfma_f32_16x16x32_bf16 v[96:99], v[140:143], v[174:177], v[96:99]
	v_mfma_f32_16x16x32_bf16 v[84:87], v[132:135], v[182:185], v[84:87]
	v_mfma_f32_16x16x32_bf16 v[80:83], v[140:143], v[182:185], v[80:83]
	v_mfma_f32_16x16x32_bf16 v[68:71], v[132:135], v[190:193], v[68:71]
	v_mfma_f32_16x16x32_bf16 v[64:67], v[140:143], v[190:193], v[64:67]
	s_setprio 0
	s_barrier
	s_add_i32 s0, vcc_hi, s20
	v_lshl_add_u64 v[214:215], s[8:9], 0, v[198:199]
	s_mov_b32 m0, s0
	ds_read_b128 v[186:189], v223 offset:16384
	ds_read_b128 v[190:193], v223 offset:17408
	ds_read_b128 v[178:181], v223 offset:18432
	ds_read_b128 v[182:185], v223 offset:19456
	ds_read_b128 v[170:173], v223 offset:20480
	ds_read_b128 v[174:177], v223 offset:21504
	ds_read_b128 v[162:165], v223 offset:22528
	ds_read_b128 v[166:169], v223 offset:23552
	global_load_lds_dwordx4 v[214:215], off
	s_add_i32 m0, s0, 0x2000
	s_add_u32 s0, s8, 0x40000
	v_lshl_add_u64 v[216:217], s[8:9], 0, v[194:195]
	s_addc_u32 s1, s9, 0
	s_add_i32 s55, s55, s20
	global_load_lds_dwordx4 v[216:217], off
	v_lshl_add_u64 v[218:219], s[0:1], 0, v[198:199]
	s_mov_b32 m0, s55
	v_lshl_add_u64 v[220:221], s[10:11], 0, v[196:197]
	global_load_lds_dwordx4 v[218:219], off
	v_lshl_add_u64 v[218:219], s[0:1], 0, v[194:195]
	s_add_i32 m0, s55, 0x2000
	v_cndmask_b32_e64 v160, 0, 1, s[4:5]
	global_load_lds_dwordx4 v[218:219], off
	v_lshl_add_u64 v[218:219], s[10:11], 0, v[200:201]
	s_mov_b32 m0, s21
	v_cmp_ne_u32_e64 s[0:1], 1, v160
	global_load_lds_dwordx4 v[218:219], off
	s_mov_b32 m0, s42
	s_andn2_b64 vcc, exec, s[4:5]
	global_load_lds_dwordx4 v[220:221], off
	s_waitcnt vmcnt(24)
	s_waitcnt lgkmcnt(0)
	s_barrier
	s_cbranch_vccnz .Lp6_724
	s_setprio 1
	v_mfma_f32_16x16x32_bf16 v[60:63], v[144:147], v[186:189], v[60:63]
	v_mfma_f32_16x16x32_bf16 v[56:59], v[152:155], v[186:189], v[56:59]
	v_mfma_f32_16x16x32_bf16 v[44:47], v[144:147], v[178:181], v[44:47]
	v_mfma_f32_16x16x32_bf16 v[40:43], v[152:155], v[178:181], v[40:43]
	v_mfma_f32_16x16x32_bf16 v[28:31], v[144:147], v[170:173], v[28:31]
	v_mfma_f32_16x16x32_bf16 v[24:27], v[152:155], v[170:173], v[24:27]
	v_mfma_f32_16x16x32_bf16 v[12:15], v[144:147], v[162:165], v[12:15]
	v_mfma_f32_16x16x32_bf16 v[8:11], v[152:155], v[162:165], v[8:11]
	v_mfma_f32_16x16x32_bf16 v[60:63], v[148:151], v[190:193], v[60:63]
	v_mfma_f32_16x16x32_bf16 v[56:59], v[156:159], v[190:193], v[56:59]
	v_mfma_f32_16x16x32_bf16 v[44:47], v[148:151], v[182:185], v[44:47]
	v_mfma_f32_16x16x32_bf16 v[40:43], v[156:159], v[182:185], v[40:43]
	v_mfma_f32_16x16x32_bf16 v[28:31], v[148:151], v[174:177], v[28:31]
	v_mfma_f32_16x16x32_bf16 v[24:27], v[156:159], v[174:177], v[24:27]
	v_mfma_f32_16x16x32_bf16 v[12:15], v[148:151], v[166:169], v[12:15]
	v_mfma_f32_16x16x32_bf16 v[8:11], v[156:159], v[166:169], v[8:11]
	s_setprio 0
	s_setprio 1
	v_mfma_f32_16x16x32_bf16 v[52:55], v[128:131], v[186:189], v[52:55]
	v_mfma_f32_16x16x32_bf16 v[48:51], v[136:139], v[186:189], v[48:51]
	v_mfma_f32_16x16x32_bf16 v[36:39], v[128:131], v[178:181], v[36:39]
	v_mfma_f32_16x16x32_bf16 v[32:35], v[136:139], v[178:181], v[32:35]
	v_mfma_f32_16x16x32_bf16 v[20:23], v[128:131], v[170:173], v[20:23]
	v_mfma_f32_16x16x32_bf16 v[16:19], v[136:139], v[170:173], v[16:19]
	v_mfma_f32_16x16x32_bf16 v[4:7], v[128:131], v[162:165], v[4:7]
	v_mfma_f32_16x16x32_bf16 v[0:3], v[136:139], v[162:165], v[0:3]
	v_mfma_f32_16x16x32_bf16 v[52:55], v[132:135], v[190:193], v[52:55]
	v_mfma_f32_16x16x32_bf16 v[48:51], v[140:143], v[190:193], v[48:51]
	v_mfma_f32_16x16x32_bf16 v[36:39], v[132:135], v[182:185], v[36:39]
	v_mfma_f32_16x16x32_bf16 v[32:35], v[140:143], v[182:185], v[32:35]
	v_mfma_f32_16x16x32_bf16 v[20:23], v[132:135], v[174:177], v[20:23]
	v_mfma_f32_16x16x32_bf16 v[16:19], v[140:143], v[174:177], v[16:19]
	v_mfma_f32_16x16x32_bf16 v[4:7], v[132:135], v[166:169], v[4:7]
	v_mfma_f32_16x16x32_bf16 v[0:3], v[140:143], v[166:169], v[0:3]
	s_setprio 0
